# P3b: touch next chunk's S-state lines (64 KB/CU) right after the first chunk's load barrier (cache prefetch of the next unit)
# speedup vs baseline: 1.0013x; 1.0013x over previous
; DI void gla_out_unit(int chunk, const Params& p, LAS unsigned char* lds) {
;     ...
;     const int h = wid >> 1, cb = wid & 1, bh = b * 4 + h, tok = tok0 + 32 * cb + r32;
;     bf16x8 qf[4], kf[2][4], sf[4][4];
; #pragma unroll
;     for (int ks = 0; ks < 4; ++ks) qf[ks] = *(const bf16x8*)(proj + (size_t)tok * NPROJ + C_GQ + h * 64 + 16 * ks + 8 * hi);
; #pragma unroll
;     for (int sb = 0; sb < 2; ++sb)
; #pragma unroll
;         for (int ks = 0; ks < 4; ++ks) kf[sb][ks] = *(const bf16x8*)(proj + (size_t)(tok0 + 32 * sb + r32) * NPROJ + C_GK + h * 64 + 16 * ks + 8 * hi);
;     const bf16_t* sp = (const bf16_t*)(p.ws + WS_SPT) + ((size_t)bh * 128 + n) * 8192;
; #pragma unroll
;     for (int vb = 0; vb < 4; ++vb)
; #pragma unroll
;         for (int ks = 0; ks < 4; ++ks) sf[vb][ks] = *(const bf16x8*)(sp + (32 * vb + r32) * 64 + 16 * ks + 8 * hi);
;     u32x2 gwv[4][4];
; #pragma unroll
;     for (int vb = 0; vb < 4; ++vb)
; #pragma unroll
;         for (int g = 0; g < 4; ++g) gwv[vb][g] = *(const u32x2*)(proj + (size_t)tok * NPROJ + C_GR + h * 128 + 32 * vb + 8 * g + 4 * hi);
;     stage_vT(proj, tok0, lds, tid);
.LBB0_618:
	v_mov_b32_e32 v202, v208
	s_ashr_i32 s8, s12, 5
	v_readfirstlane_b32 s13, v202
	s_and_b32 s21, s8, -4
	s_lshr_b32 s8, s13, 1
	s_and_b32 s8, s8, 32
	v_and_b32_e32 v199, 31, v202
	s_add_i32 s8, s0, s8
	v_add_u32_e32 v198, s8, v199
	s_ashr_i32 s20, s13, 7
	v_mad_i64_i32 v[68:69], s[8:9], v198, s5, v[160:161]
	s_lshl_b32 s8, s20, 6
	s_ashr_i32 s9, s8, 31
	v_bfe_u32 v70, v202, 5, 1
	s_lshl_b64 s[8:9], s[8:9], 1
	v_lshl_add_u64 v[0:1], v[68:69], 0, s[8:9]
	v_lshlrev_b32_e32 v4, 4, v70
	v_mov_b32_e32 v5, v167
	v_lshl_add_u64 v[0:1], v[0:1], 0, v[4:5]
	v_add_u32_e32 v8, s0, v199
	global_load_dwordx4 v[140:143], v[0:1], off offset:3072
	global_load_dwordx4 v[136:139], v[0:1], off offset:3104
	global_load_dwordx4 v[132:135], v[0:1], off offset:3136
	global_load_dwordx4 v[128:131], v[0:1], off offset:3168
	v_mad_i64_i32 v[0:1], s[18:19], v8, s5, v[160:161]
	v_lshl_add_u64 v[0:1], v[0:1], 0, s[8:9]
	v_lshl_add_u64 v[6:7], v[0:1], 0, v[4:5]
	global_load_dwordx4 v[0:3], v[6:7], off offset:3584
	global_load_dwordx4 v[24:27], v[6:7], off offset:3616
	global_load_dwordx4 v[20:23], v[6:7], off offset:3648
	global_load_dwordx4 v[16:19], v[6:7], off offset:3680
	v_add_u32_e32 v6, 32, v8
	v_mad_i64_i32 v[6:7], s[18:19], v6, s5, v[160:161]
	v_lshl_add_u64 v[6:7], v[6:7], 0, s[8:9]
	s_add_i32 s8, s20, s21
	s_ashr_i32 s9, s8, 31
	s_and_b32 s18, s1, 0xfe000
	s_lshl_b64 s[8:9], s[8:9], 21
	s_add_u32 s8, s94, s8
	s_addc_u32 s9, s95, s9
	s_lshl_b32 s18, s18, 1
	s_add_u32 s8, s8, s18
	v_lshl_add_u64 v[6:7], v[6:7], 0, v[4:5]
	s_addc_u32 s9, s9, 0
	global_load_dwordx4 v[156:159], v[6:7], off offset:3584
	global_load_dwordx4 v[152:155], v[6:7], off offset:3616
	global_load_dwordx4 v[148:151], v[6:7], off offset:3648
	global_load_dwordx4 v[144:147], v[6:7], off offset:3680
	v_lshl_add_u64 v[4:5], s[8:9], 0, v[4:5]
	v_lshlrev_b32_e32 v6, 7, v199
	v_mov_b32_e32 v7, v167
	v_lshl_add_u64 v[4:5], v[4:5], 0, v[6:7]
	v_add_co_u32_e32 v6, vcc, s6, v4
	s_movk_i32 s8, 0x2000
	s_nop 0
	v_addc_co_u32_e32 v7, vcc, 0, v5, vcc
	v_add_co_u32_e32 v8, vcc, s8, v4
	s_and_b32 s22, s13, 0xffffff80
	s_nop 0
	v_addc_co_u32_e32 v9, vcc, 0, v5, vcc
	s_movk_i32 s8, 0x3000
	s_ashr_i32 s23, s22, 31
	v_lshlrev_b32_e32 v166, 3, v70
	global_load_dwordx4 v[64:67], v[4:5], off
	global_load_dwordx4 v[88:91], v[4:5], off offset:32
	global_load_dwordx4 v[84:87], v[4:5], off offset:64
	global_load_dwordx4 v[80:83], v[4:5], off offset:96
	v_add_co_u32_e32 v4, vcc, s8, v4
	v_lshl_add_u64 v[68:69], s[22:23], 1, v[68:69]
	s_nop 0
	v_addc_co_u32_e32 v5, vcc, 0, v5, vcc
	v_lshl_add_u64 v[68:69], v[68:69], 0, v[166:167]
	s_mov_b64 s[8:9], 0x1400
	v_lshlrev_b32_e32 v203, 2, v70
	v_lshl_add_u64 v[70:71], v[68:69], 0, s[8:9]
	v_add_co_u32_e32 v68, vcc, s6, v68
	s_waitcnt vmcnt(48)
	v_ashrrev_i32_e32 v113, 6, v202
	v_addc_co_u32_e32 v69, vcc, 0, v69, vcc
	global_load_dwordx4 v[60:63], v[8:9], off offset:-4096
	global_load_dwordx4 v[56:59], v[6:7], off offset:32
	global_load_dwordx4 v[52:55], v[6:7], off offset:64
	global_load_dwordx4 v[48:51], v[6:7], off offset:96
	global_load_dwordx4 v[44:47], v[8:9], off
	global_load_dwordx4 v[40:43], v[8:9], off offset:32
	global_load_dwordx4 v[36:39], v[8:9], off offset:64
	global_load_dwordx4 v[32:35], v[8:9], off offset:96
	global_load_dwordx4 v[28:31], v[4:5], off
	global_load_dwordx4 v[12:15], v[4:5], off offset:32
	s_nop 0
	global_load_dwordx4 v[8:11], v[4:5], off offset:64
	s_nop 0
	global_load_dwordx4 v[4:7], v[4:5], off offset:96
	s_nop 0
	global_load_dwordx2 v[200:201], v[68:69], off offset:1024
	global_load_dwordx2 v[196:197], v[70:71], off offset:16
	global_load_dwordx2 v[194:195], v[70:71], off offset:32
	global_load_dwordx2 v[192:193], v[70:71], off offset:48
	global_load_dwordx2 v[190:191], v[70:71], off offset:64
	global_load_dwordx2 v[188:189], v[70:71], off offset:80
	global_load_dwordx2 v[186:187], v[70:71], off offset:96
	global_load_dwordx2 v[184:185], v[70:71], off offset:112
	global_load_dwordx2 v[182:183], v[70:71], off offset:128
	global_load_dwordx2 v[180:181], v[70:71], off offset:144
	global_load_dwordx2 v[178:179], v[70:71], off offset:160
	global_load_dwordx2 v[176:177], v[70:71], off offset:176
	global_load_dwordx2 v[174:175], v[70:71], off offset:192
	global_load_dwordx2 v[172:173], v[70:71], off offset:208
	global_load_dwordx2 v[170:171], v[70:71], off offset:224
	global_load_dwordx2 v[168:169], v[70:71], off offset:240
	v_add_u32_e32 v68, s0, v113
	v_lshlrev_b32_e32 v70, 4, v202
	v_add_u32_e32 v72, 0x200, v202
	v_mad_i64_i32 v[68:69], s[8:9], v68, s5, v[160:161]
	v_and_b32_e32 v166, 0x3f0, v70
	v_ashrrev_i32_e32 v116, 6, v72
	v_lshl_add_u64 v[68:69], v[68:69], 0, v[166:167]
	v_add_u32_e32 v72, s0, v116
	v_add_u32_e32 v76, 0x400, v202
	v_add_co_u32_e32 v68, vcc, s6, v68
	v_mad_i64_i32 v[72:73], s[8:9], v72, s5, v[160:161]
	v_ashrrev_i32_e32 v117, 6, v76
	v_addc_co_u32_e32 v69, vcc, 0, v69, vcc
	v_lshl_add_u64 v[72:73], v[72:73], 0, v[166:167]
	v_add_u32_e32 v76, s0, v117
	v_add_u32_e32 v92, 0x600, v202
	v_add_co_u32_e32 v72, vcc, s6, v72
	v_mad_i64_i32 v[76:77], s[8:9], v76, s5, v[160:161]
	v_ashrrev_i32_e32 v118, 6, v92
	v_addc_co_u32_e32 v73, vcc, 0, v73, vcc
	v_lshl_add_u64 v[76:77], v[76:77], 0, v[166:167]
	v_add_u32_e32 v92, s0, v118
	v_add_u32_e32 v96, 0x800, v202
	v_add_co_u32_e32 v76, vcc, s6, v76
	v_mad_i64_i32 v[92:93], s[8:9], v92, s5, v[160:161]
	v_ashrrev_i32_e32 v119, 6, v96
	v_addc_co_u32_e32 v77, vcc, 0, v77, vcc
	v_lshl_add_u64 v[92:93], v[92:93], 0, v[166:167]
	v_add_u32_e32 v96, s0, v119
	v_add_u32_e32 v100, 0xa00, v202
	v_add_co_u32_e32 v92, vcc, s6, v92
	v_mad_i64_i32 v[96:97], s[8:9], v96, s5, v[160:161]
; DI int crow(int r, int hi) { return (r & 3) + 8 * (r >> 2) + 4 * hi; }
; DI void gla_out_unit(int chunk, const Params& p, LAS unsigned char* lds) {
;     ...
;     stage_vT(proj, tok0, lds, tid);
;     __syncthreads();
;     f32x16 oT[4];
; #pragma unroll
;     for (int vb = 0; vb < 4; ++vb)
; #pragma unroll
;         for (int e = 0; e < 16; ++e) oT[vb][e] = 0.f;
; #pragma unroll
;     for (int vb = 0; vb < 4; ++vb)
; #pragma unroll
;         for (int ks = 0; ks < 4; ++ks) oT[vb] = __builtin_amdgcn_mfma_f32_32x32x16_bf16(sf[vb][ks], qf[ks], oT[vb], 0, 0, 0);
; #pragma unroll
;     for (int sb = 0; sb < 2; ++sb) {
;         if (sb <= cb) {
;         f32x16 X;
; #pragma unroll
;         for (int e = 0; e < 16; ++e) X[e] = 0.f;
; #pragma unroll
;         for (int ks = 0; ks < 4; ++ks) X = __builtin_amdgcn_mfma_f32_32x32x16_bf16(kf[sb][ks], qf[ks], X, 0, 0, 0);
;         if (sb == cb) {
; #pragma unroll
;             for (int i = 0; i < 16; ++i) if (crow(i, hi) > r32) X[i] = 0.f; }
	v_ashrrev_i32_e32 v120, 6, v100
	v_addc_co_u32_e32 v93, vcc, 0, v93, vcc
	v_lshl_add_u64 v[96:97], v[96:97], 0, v[166:167]
	v_add_u32_e32 v100, s0, v120
	v_add_u32_e32 v104, 0xc00, v202
	v_add_co_u32_e32 v96, vcc, s6, v96
	v_mad_i64_i32 v[100:101], s[8:9], v100, s5, v[160:161]
	v_ashrrev_i32_e32 v121, 6, v104
	global_load_dwordx4 v[68:71], v[68:69], off
	v_addc_co_u32_e32 v97, vcc, 0, v97, vcc
	v_lshl_add_u64 v[100:101], v[100:101], 0, v[166:167]
	v_add_u32_e32 v104, s0, v121
	v_add_u32_e32 v108, 0xe00, v202
	global_load_dwordx4 v[72:75], v[72:73], off
	v_add_co_u32_e32 v100, vcc, s6, v100
	v_mad_i64_i32 v[104:105], s[8:9], v104, s5, v[160:161]
	v_ashrrev_i32_e32 v122, 6, v108
	global_load_dwordx4 v[76:79], v[76:77], off
	v_addc_co_u32_e32 v101, vcc, 0, v101, vcc
	v_lshl_add_u64 v[104:105], v[104:105], 0, v[166:167]
	v_add_u32_e32 v108, s0, v122
	global_load_dwordx4 v[92:95], v[92:93], off
	v_add_co_u32_e32 v104, vcc, s6, v104
	v_mad_i64_i32 v[108:109], s[8:9], v108, s5, v[160:161]
	global_load_dwordx4 v[96:99], v[96:97], off
	v_addc_co_u32_e32 v105, vcc, 0, v105, vcc
	v_lshl_add_u64 v[108:109], v[108:109], 0, v[166:167]
	global_load_dwordx4 v[100:103], v[100:101], off
	v_add_co_u32_e32 v108, vcc, s6, v108
	global_load_dwordx4 v[104:107], v[104:105], off
	s_nop 0
	v_addc_co_u32_e32 v109, vcc, 0, v109, vcc
	global_load_dwordx4 v[108:111], v[108:109], off
	v_add_u32_e32 v112, 0, v166
	v_mad_u64_u32 v[114:115], s[8:9], v113, s7, v[112:113]
	s_bitcmp1_b32 s13, 6
	s_cselect_b64 s[20:21], -1, 0
	s_and_b64 vcc, exec, s[20:21]
	v_cmp_le_u32_e64 s[40:41], v203, v199
	v_cmp_lt_u32_e64 s[42:43], v203, v199
	v_or_b32_e32 v222, 2, v203
	v_or_b32_e32 v221, 3, v203
	v_or_b32_e32 v166, 8, v203
	v_or_b32_e32 v220, 9, v203
	v_or_b32_e32 v219, 10, v203
	v_or_b32_e32 v218, 11, v203
	v_or_b32_e32 v205, 16, v203
	v_or_b32_e32 v217, 17, v203
	v_or_b32_e32 v216, 18, v203
	v_or_b32_e32 v215, 19, v203
	v_or_b32_e32 v207, 24, v203
	v_or_b32_e32 v214, 25, v203
	v_or_b32_e32 v213, 26, v203
	v_or_b32_e32 v212, 27, v203
	s_waitcnt vmcnt(7)
	ds_write_b128 v114, v[68:71]
	v_mad_u64_u32 v[68:69], s[8:9], v116, s7, v[112:113]
	s_waitcnt vmcnt(6)
	ds_write_b128 v68, v[72:75]
	v_mad_u64_u32 v[68:69], s[8:9], v117, s7, v[112:113]
	s_waitcnt vmcnt(5)
	ds_write_b128 v68, v[76:79]
	v_mad_u64_u32 v[68:69], s[8:9], v118, s7, v[112:113]
	s_waitcnt vmcnt(4)
	ds_write_b128 v68, v[92:95]
	v_mad_u64_u32 v[68:69], s[8:9], v119, s7, v[112:113]
	s_waitcnt vmcnt(3)
	ds_write_b128 v68, v[96:99]
	v_mad_u64_u32 v[68:69], s[8:9], v120, s7, v[112:113]
	s_waitcnt vmcnt(2)
	ds_write_b128 v68, v[100:103]
	v_mad_u64_u32 v[68:69], s[8:9], v121, s7, v[112:113]
	s_waitcnt vmcnt(1)
	ds_write_b128 v68, v[104:107]
	v_mad_u64_u32 v[68:69], s[8:9], v122, s7, v[112:113]
	s_waitcnt vmcnt(0)
	ds_write_b128 v68, v[108:111]
	v_mfma_f32_32x32x16_bf16 v[64:79], v[64:67], v[140:143], 0
	s_waitcnt lgkmcnt(0)
	s_barrier
	s_add_i32 s8, s12, s92
	s_cmpk_gt_i32 s8, 0x1ff
	s_cbranch_scc1 .Lp3b_pf_done
	s_ashr_i32 s9, s8, 5
	s_and_b32 s9, s9, -4
	v_lshrrev_b32_e32 v226, 7, v208
	v_add_u32_e32 v226, s9, v226
	v_lshlrev_b32_e32 v226, 21, v226
	s_and_b32 s9, s8, 0x7f
	s_lshl_b32 s9, s9, 14
	v_and_b32_e32 v227, 0x7f, v208
	v_lshl_add_u32 v227, v227, 7, s9
	v_add_u32_e32 v226, v226, v227
	v_mov_b32_e32 v227, 0
	v_lshl_add_u64 v[226:227], s[94:95], 0, v[226:227]
	global_load_dword v229, v[226:227], off
.Lp3b_pf_done:
	v_mfma_f32_32x32x16_bf16 v[112:127], v[28:31], v[140:143], 0
	v_mfma_f32_32x32x16_bf16 v[64:79], v[88:91], v[136:139], v[64:79]
	v_mfma_f32_32x32x16_bf16 v[112:127], v[12:15], v[136:139], v[112:127]
	v_mfma_f32_32x32x16_bf16 v[64:79], v[84:87], v[132:135], v[64:79]
	v_mfma_f32_32x32x16_bf16 v[112:127], v[8:11], v[132:135], v[112:127]
	v_mfma_f32_32x32x16_bf16 v[64:79], v[80:83], v[128:131], v[64:79]
	v_mfma_f32_32x32x16_bf16 v[80:95], v[60:63], v[140:143], 0
	v_mfma_f32_32x32x16_bf16 v[96:111], v[44:47], v[140:143], 0
	v_mfma_f32_32x32x16_bf16 v[112:127], v[4:7], v[128:131], v[112:127]
	v_mfma_f32_32x32x16_bf16 v[0:15], v[0:3], v[140:143], 0
	v_mfma_f32_32x32x16_bf16 v[80:95], v[56:59], v[136:139], v[80:95]
	v_mfma_f32_32x32x16_bf16 v[96:111], v[40:43], v[136:139], v[96:111]
	v_mfma_f32_32x32x16_bf16 v[0:15], v[24:27], v[136:139], v[0:15]
	v_mfma_f32_32x32x16_bf16 v[80:95], v[52:55], v[132:135], v[80:95]
	v_mfma_f32_32x32x16_bf16 v[96:111], v[36:39], v[132:135], v[96:111]
	v_mfma_f32_32x32x16_bf16 v[0:15], v[20:23], v[132:135], v[0:15]
	v_mfma_f32_32x32x16_bf16 v[80:95], v[48:51], v[128:131], v[80:95]
	v_mfma_f32_32x32x16_bf16 v[96:111], v[32:35], v[128:131], v[96:111]
	v_mfma_f32_32x32x16_bf16 v[0:15], v[16:19], v[128:131], v[0:15]
	s_cbranch_vccnz .LBB0_620
	v_cmp_le_u32_e32 vcc, v222, v199
	v_or_b32_e32 v16, 8, v203
	s_nop 8
	v_cndmask_b32_e64 v1, 0, v1, s[42:43]
	v_cndmask_b32_e32 v2, 0, v2, vcc
	v_cmp_le_u32_e32 vcc, v221, v199
	v_cndmask_b32_e64 v0, 0, v0, s[40:41]
	s_nop 0
	v_cndmask_b32_e32 v3, 0, v3, vcc
	v_cmp_le_u32_e32 vcc, v16, v199
	v_or_b32_e32 v16, 16, v203
	s_nop 0
	v_cndmask_b32_e32 v4, 0, v4, vcc
	v_cmp_le_u32_e32 vcc, v220, v199
	s_nop 1
	v_cndmask_b32_e32 v5, 0, v5, vcc
	v_cmp_le_u32_e32 vcc, v219, v199
	s_nop 1
	v_cndmask_b32_e32 v6, 0, v6, vcc
	v_cmp_le_u32_e32 vcc, v218, v199
	s_nop 1
	v_cndmask_b32_e32 v7, 0, v7, vcc
	v_cmp_le_u32_e32 vcc, v16, v199
	v_or_b32_e32 v16, 24, v203
	s_nop 0
	v_cndmask_b32_e32 v8, 0, v8, vcc
	v_cmp_le_u32_e32 vcc, v217, v199
	s_nop 1
	v_cndmask_b32_e32 v9, 0, v9, vcc
	v_cmp_le_u32_e32 vcc, v216, v199
	s_nop 1
	v_cndmask_b32_e32 v10, 0, v10, vcc
	v_cmp_le_u32_e32 vcc, v215, v199
	s_nop 1
	v_cndmask_b32_e32 v11, 0, v11, vcc
	v_cmp_le_u32_e32 vcc, v16, v199
	s_nop 1
	v_cndmask_b32_e32 v12, 0, v12, vcc
	v_cmp_le_u32_e32 vcc, v214, v199
	s_nop 1
	v_cndmask_b32_e32 v13, 0, v13, vcc
	v_cmp_le_u32_e32 vcc, v213, v199
	s_nop 1
	v_cndmask_b32_e32 v14, 0, v14, vcc
	v_cmp_le_u32_e32 vcc, v212, v199
	s_nop 1
	v_cndmask_b32_e32 v15, 0, v15, vcc
